# P5 residual epilogue: next round's residual loads issued before the current round's stores (counted vmcnt waits)
# speedup vs baseline: 1.0024x; 1.0024x over previous
; __device__ __forceinline__ float bflo(unsigned u) { return __uint_as_float(u << 16); }
; __device__ __forceinline__ float bfhi(unsigned u) { return __uint_as_float(u & 0xffff0000u); }
; __device__ __forceinline__ float dot4(f32x4 v) { return (v[0] * v[0] + v[1] * v[1]) + (v[2] * v[2] + v[3] * v[3]); }
; __device__ __forceinline__ u32x2 pack4(f32x4 v) { u32x2 w; w.x = cvt_pk_bf16(v[0], v[1]); w.y = cvt_pk_bf16(v[2], v[3]); return w; }
; __device__ __forceinline__ float quad_sum(float s) { s += __shfl_xor(s, 16); s += __shfl_xor(s, 32); return s; }
; template <int EK>
; __device__ __forceinline__ void epi_tile(const f32x4 (&acc)[2][2][4][2], const Unit& u, int wr, int wc, int fr, int fq, const EpiArgs& E, const LAS float* rt) {
;     ...
;             } else {
;                 float ss = 0.f;
; #pragma unroll
;                 for (int bj = 0; bj < 2; ++bj) { const int col = u.pn * BM + bj * HALF + wc * 32 + fq * 8;
;                     const u32x4 rb = *(const u32x4*)(E.res + (size_t)row * 1024 + col);
;                     const f32x4 x0 = (f32x4){bflo(rb.x), bfhi(rb.x), bflo(rb.y), bfhi(rb.y)} + acc[ai][bj][m][0];
;                     const f32x4 x1 = (f32x4){bflo(rb.z), bfhi(rb.z), bflo(rb.w), bfhi(rb.w)} + acc[ai][bj][m][1]; ss += dot4(x0) + dot4(x1);
;                     const u32x2 lo = pack4(x0), hi = pack4(x1);
;                     *(u32x4*)(E.ob + (size_t)row * 1024 + col) = (u32x4){lo.x, lo.y, hi.x, hi.y}; }
;                 ss = quad_sum(ss); if (fq == 0) E.stOut[(size_t)row * 16 + u.pn * 4 + wc] = ss;
.LBB0_796:
	v_lshl_add_u32 v148, s3, 8, v1
	v_ashrrev_i32_e32 v149, 31, v148
	v_lshl_or_b32 v146, s45, 8, v153
	v_lshlrev_b64 v[150:151], 11, v[148:149]
	v_lshl_add_u64 v[150:151], s[62:63], 0, v[150:151]
	v_ashrrev_i32_e32 v147, 31, v146
	v_lshl_add_u64 v[166:167], v[146:147], 1, v[150:151]
	global_load_dwordx4 v[158:161], v[166:167], off
	global_load_dwordx4 v[162:165], v[166:167], off offset:256
	v_mov_b64_e32 v[200:201], v[166:167]
	s_mov_b64 s[98:99], 0x8000
	v_lshl_add_u64 v[202:203], v[200:201], 0, s[98:99]
	global_load_dwordx4 v[184:187], v[202:203], off
	global_load_dwordx4 v[188:191], v[202:203], off offset:256
	v_and_b32_e32 v151, 64, v155
	v_xor_b32_e32 v150, 16, v155
	v_add_u32_e32 v151, 64, v151
	v_xor_b32_e32 v156, 32, v155
	v_cmp_lt_i32_e32 vcc, v150, v151
	s_lshl_b32 s38, s45, 2
	s_ashr_i32 s39, s38, 31
	v_cndmask_b32_e32 v150, v155, v150, vcc
	v_cmp_lt_i32_e32 vcc, v156, v151
	s_waitcnt vmcnt(2)
	v_and_b32_e32 v151, 0xffff0000, v158
	v_cndmask_b32_e32 v157, v155, v156, vcc
	v_lshlrev_b32_e32 v156, 2, v150
	v_lshlrev_b32_e32 v150, 16, v158
	v_lshlrev_b32_e32 v158, 16, v159
	v_and_b32_e32 v159, 0xffff0000, v159
	v_lshlrev_b32_e32 v168, 16, v160
	v_and_b32_e32 v169, 0xffff0000, v160
	v_lshlrev_b32_e32 v160, 16, v161
	v_and_b32_e32 v161, 0xffff0000, v161
	v_lshlrev_b32_e32 v170, 16, v162
	v_and_b32_e32 v171, 0xffff0000, v162
	v_lshlrev_b32_e32 v162, 16, v163
	v_and_b32_e32 v163, 0xffff0000, v163
	v_lshlrev_b32_e32 v172, 16, v164
	v_and_b32_e32 v173, 0xffff0000, v164
	v_lshlrev_b32_e32 v164, 16, v165
	v_and_b32_e32 v165, 0xffff0000, v165
	v_pk_add_f32 v[174:175], v[128:129], v[158:159]
	v_pk_add_f32 v[150:151], v[126:127], v[150:151]
	v_pk_add_f32 v[176:177], v[124:125], v[160:161]
	v_pk_add_f32 v[160:161], v[122:123], v[168:169]
	v_pk_add_f32 v[168:169], v[96:97], v[162:163]
	v_pk_add_f32 v[162:163], v[94:95], v[170:171]
	v_pk_add_f32 v[170:171], v[92:93], v[164:165]
	v_pk_add_f32 v[164:165], v[90:91], v[172:173]
	v_mul_f32_e32 v172, v151, v151
	v_mul_f32_e32 v173, v175, v175
	v_mul_f32_e32 v178, v161, v161
	v_mul_f32_e32 v179, v177, v177
	v_cvt_pk_bf16_f32 v158, v150, v151
	v_cvt_pk_bf16_f32 v159, v174, v175
	v_mul_f32_e32 v151, v163, v163
	v_mul_f32_e32 v175, v169, v169
	v_mul_f32_e32 v180, v165, v165
	v_mul_f32_e32 v181, v171, v171
	v_fmac_f32_e32 v172, v150, v150
	v_fmac_f32_e32 v173, v174, v174
	v_fmac_f32_e32 v178, v160, v160
	v_fmac_f32_e32 v179, v176, v176
	v_fmac_f32_e32 v151, v162, v162
	v_fmac_f32_e32 v175, v168, v168
	v_fmac_f32_e32 v180, v164, v164
	v_fmac_f32_e32 v181, v170, v170
	v_add_f32_e32 v150, v172, v173
	v_add_f32_e32 v172, v178, v179
	v_add_f32_e32 v151, v151, v175
	v_add_f32_e32 v173, v180, v181
	v_add_f32_e32 v150, v150, v172
	v_add_f32_e32 v151, v151, v173
	v_add_f32_e32 v150, v150, v151
	ds_bpermute_b32 v151, v156, v150
	v_lshlrev_b32_e32 v157, 2, v157
	v_cvt_pk_bf16_f32 v160, v160, v161
	v_cvt_pk_bf16_f32 v161, v176, v177
	v_cvt_pk_bf16_f32 v162, v162, v163
	s_waitcnt lgkmcnt(0)
	v_add_f32_e32 v150, v150, v151
	ds_bpermute_b32 v151, v157, v150
	global_store_dwordx4 v[166:167], v[158:161], off
	v_cvt_pk_bf16_f32 v163, v168, v169
	v_cvt_pk_bf16_f32 v164, v164, v165
	v_cvt_pk_bf16_f32 v165, v170, v171
	global_store_dwordx4 v[166:167], v[162:165], off offset:256
	s_and_saveexec_b64 s[40:41], s[4:5]
	s_cbranch_execz .LBB0_798
	v_lshlrev_b64 v[158:159], 6, v[148:149]
	v_lshl_add_u64 v[158:159], s[16:17], 0, v[158:159]
	v_lshl_add_u64 v[158:159], s[38:39], 2, v[158:159]
	s_lshl_b32 s20, s59, 2
	v_lshl_add_u64 v[158:159], v[158:159], 0, s[20:21]
	s_waitcnt lgkmcnt(0)
	v_add_f32_e32 v149, v150, v151
	global_store_dword v[158:159], v149, off
.LBB0_798:
	s_or_b64 exec, exec, s[40:41]
	v_or_b32_e32 v150, 16, v148
	s_waitcnt lgkmcnt(0)
	v_ashrrev_i32_e32 v151, 31, v150
	v_lshlrev_b64 v[158:159], 11, v[150:151]
	v_lshl_add_u64 v[158:159], s[62:63], 0, v[158:159]
	v_lshl_add_u64 v[166:167], v[146:147], 1, v[158:159]
	s_mov_b64 s[98:99], 0x10000
	v_lshl_add_u64 v[202:203], v[200:201], 0, s[98:99]
	global_load_dwordx4 v[192:195], v[202:203], off
	global_load_dwordx4 v[196:199], v[202:203], off offset:256
	s_waitcnt vmcnt(5)
	v_mov_b32_e32 v158, v184
	v_mov_b32_e32 v159, v185
	v_mov_b32_e32 v160, v186
	v_mov_b32_e32 v161, v187
	v_lshlrev_b32_e32 v168, 16, v158
	v_and_b32_e32 v169, 0xffff0000, v158
	v_lshlrev_b32_e32 v158, 16, v159
	v_and_b32_e32 v159, 0xffff0000, v159
	v_lshlrev_b32_e32 v170, 16, v160
	v_and_b32_e32 v171, 0xffff0000, v160
	v_lshlrev_b32_e32 v160, 16, v161
	v_and_b32_e32 v161, 0xffff0000, v161
	v_mov_b32_e32 v162, v188
	v_mov_b32_e32 v163, v189
	v_mov_b32_e32 v164, v190
	v_mov_b32_e32 v165, v191
	v_lshlrev_b32_e32 v172, 16, v162
	v_and_b32_e32 v173, 0xffff0000, v162
	v_lshlrev_b32_e32 v162, 16, v163
	v_and_b32_e32 v163, 0xffff0000, v163
	v_lshlrev_b32_e32 v174, 16, v164
	v_and_b32_e32 v175, 0xffff0000, v164
	v_lshlrev_b32_e32 v164, 16, v165
	v_and_b32_e32 v165, 0xffff0000, v165
	v_pk_add_f32 v[176:177], v[120:121], v[158:159]
	v_pk_add_f32 v[168:169], v[118:119], v[168:169]
	v_pk_add_f32 v[178:179], v[116:117], v[160:161]
	v_pk_add_f32 v[160:161], v[114:115], v[170:171]
	v_pk_add_f32 v[162:163], v[88:89], v[162:163]
	v_pk_add_f32 v[170:171], v[86:87], v[172:173]
	v_pk_add_f32 v[164:165], v[84:85], v[164:165]
	v_pk_add_f32 v[172:173], v[82:83], v[174:175]
	v_mul_f32_e32 v149, v169, v169
	v_mul_f32_e32 v174, v177, v177
	v_mul_f32_e32 v175, v161, v161
	v_mul_f32_e32 v180, v179, v179
	v_cvt_pk_bf16_f32 v158, v168, v169
	v_cvt_pk_bf16_f32 v159, v176, v177
	v_mul_f32_e32 v169, v171, v171
	v_mul_f32_e32 v177, v163, v163
	v_mul_f32_e32 v181, v173, v173
	v_mul_f32_e32 v182, v165, v165
	v_fmac_f32_e32 v149, v168, v168
	v_fmac_f32_e32 v174, v176, v176
	v_fmac_f32_e32 v175, v160, v160
	v_fmac_f32_e32 v180, v178, v178
	v_fmac_f32_e32 v169, v170, v170
	v_fmac_f32_e32 v177, v162, v162
	v_fmac_f32_e32 v181, v172, v172
	v_fmac_f32_e32 v182, v164, v164
	v_add_f32_e32 v149, v149, v174
	v_add_f32_e32 v168, v175, v180
	v_add_f32_e32 v169, v169, v177
	v_add_f32_e32 v174, v181, v182
	v_add_f32_e32 v149, v149, v168
	v_add_f32_e32 v168, v169, v174
	v_add_f32_e32 v149, v149, v168
	ds_bpermute_b32 v168, v156, v149
	v_cvt_pk_bf16_f32 v160, v160, v161
	v_cvt_pk_bf16_f32 v161, v178, v179
	global_store_dwordx4 v[166:167], v[158:161], off
	s_waitcnt lgkmcnt(0)
	v_add_f32_e32 v149, v149, v168
	ds_bpermute_b32 v158, v157, v149
	v_cvt_pk_bf16_f32 v160, v170, v171
	v_cvt_pk_bf16_f32 v161, v162, v163
	v_cvt_pk_bf16_f32 v162, v172, v173
	v_cvt_pk_bf16_f32 v163, v164, v165
	global_store_dwordx4 v[166:167], v[160:163], off offset:256
	s_and_saveexec_b64 s[40:41], s[4:5]
	s_cbranch_execz .LBB0_800
	v_lshlrev_b64 v[150:151], 6, v[150:151]
	v_lshl_add_u64 v[150:151], s[16:17], 0, v[150:151]
	v_lshl_add_u64 v[150:151], s[38:39], 2, v[150:151]
	s_lshl_b32 s20, s59, 2
	v_lshl_add_u64 v[150:151], v[150:151], 0, s[20:21]
	s_waitcnt lgkmcnt(0)
	v_add_f32_e32 v149, v149, v158
	global_store_dword v[150:151], v149, off
; __device__ __forceinline__ float bflo(unsigned u) { return __uint_as_float(u << 16); }
; __device__ __forceinline__ float bfhi(unsigned u) { return __uint_as_float(u & 0xffff0000u); }
; __device__ __forceinline__ float dot4(f32x4 v) { return (v[0] * v[0] + v[1] * v[1]) + (v[2] * v[2] + v[3] * v[3]); }
; __device__ __forceinline__ u32x2 pack4(f32x4 v) { u32x2 w; w.x = cvt_pk_bf16(v[0], v[1]); w.y = cvt_pk_bf16(v[2], v[3]); return w; }
; __device__ __forceinline__ float quad_sum(float s) { s += __shfl_xor(s, 16); s += __shfl_xor(s, 32); return s; }
; template <int EK>
; __device__ __forceinline__ void epi_tile(const f32x4 (&acc)[2][2][4][2], const Unit& u, int wr, int wc, int fr, int fq, const EpiArgs& E, const LAS float* rt) {
;     ...
;             } else {
;                 float ss = 0.f;
; #pragma unroll
;                 for (int bj = 0; bj < 2; ++bj) { const int col = u.pn * BM + bj * HALF + wc * 32 + fq * 8;
;                     const u32x4 rb = *(const u32x4*)(E.res + (size_t)row * 1024 + col);
;                     const f32x4 x0 = (f32x4){bflo(rb.x), bfhi(rb.x), bflo(rb.y), bfhi(rb.y)} + acc[ai][bj][m][0];
;                     const f32x4 x1 = (f32x4){bflo(rb.z), bfhi(rb.z), bflo(rb.w), bfhi(rb.w)} + acc[ai][bj][m][1]; ss += dot4(x0) + dot4(x1);
;                     const u32x2 lo = pack4(x0), hi = pack4(x1);
;                     *(u32x4*)(E.ob + (size_t)row * 1024 + col) = (u32x4){lo.x, lo.y, hi.x, hi.y}; }
;                 ss = quad_sum(ss); if (fq == 0) E.stOut[(size_t)row * 16 + u.pn * 4 + wc] = ss;
.LBB0_800:
	s_or_b64 exec, exec, s[40:41]
	v_or_b32_e32 v150, 32, v148
	v_ashrrev_i32_e32 v151, 31, v150
	s_waitcnt lgkmcnt(0)
	v_lshlrev_b64 v[158:159], 11, v[150:151]
	v_lshl_add_u64 v[158:159], s[62:63], 0, v[158:159]
	v_lshl_add_u64 v[166:167], v[146:147], 1, v[158:159]
	s_mov_b64 s[98:99], 0x18000
	v_lshl_add_u64 v[202:203], v[200:201], 0, s[98:99]
	global_load_dwordx4 v[184:187], v[202:203], off
	global_load_dwordx4 v[188:191], v[202:203], off offset:256
	s_waitcnt vmcnt(5)
	v_mov_b32_e32 v158, v192
	v_mov_b32_e32 v159, v193
	v_mov_b32_e32 v160, v194
	v_mov_b32_e32 v161, v195
	v_lshlrev_b32_e32 v168, 16, v158
	v_and_b32_e32 v169, 0xffff0000, v158
	v_lshlrev_b32_e32 v158, 16, v159
	v_and_b32_e32 v159, 0xffff0000, v159
	v_lshlrev_b32_e32 v170, 16, v160
	v_and_b32_e32 v171, 0xffff0000, v160
	v_lshlrev_b32_e32 v160, 16, v161
	v_and_b32_e32 v161, 0xffff0000, v161
	v_mov_b32_e32 v162, v196
	v_mov_b32_e32 v163, v197
	v_mov_b32_e32 v164, v198
	v_mov_b32_e32 v165, v199
	v_lshlrev_b32_e32 v172, 16, v162
	v_and_b32_e32 v173, 0xffff0000, v162
	v_lshlrev_b32_e32 v162, 16, v163
	v_and_b32_e32 v163, 0xffff0000, v163
	v_lshlrev_b32_e32 v174, 16, v164
	v_and_b32_e32 v175, 0xffff0000, v164
	v_lshlrev_b32_e32 v164, 16, v165
	v_and_b32_e32 v165, 0xffff0000, v165
	v_pk_add_f32 v[176:177], v[112:113], v[158:159]
	v_pk_add_f32 v[168:169], v[110:111], v[168:169]
	v_pk_add_f32 v[178:179], v[108:109], v[160:161]
	v_pk_add_f32 v[160:161], v[106:107], v[170:171]
	v_pk_add_f32 v[162:163], v[80:81], v[162:163]
	v_pk_add_f32 v[170:171], v[78:79], v[172:173]
	v_pk_add_f32 v[164:165], v[76:77], v[164:165]
	v_pk_add_f32 v[172:173], v[74:75], v[174:175]
	v_mul_f32_e32 v149, v169, v169
	v_mul_f32_e32 v174, v177, v177
	v_mul_f32_e32 v175, v161, v161
	v_mul_f32_e32 v180, v179, v179
	v_cvt_pk_bf16_f32 v158, v168, v169
	v_cvt_pk_bf16_f32 v159, v176, v177
	v_mul_f32_e32 v169, v171, v171
	v_mul_f32_e32 v177, v163, v163
	v_mul_f32_e32 v181, v173, v173
	v_mul_f32_e32 v182, v165, v165
	v_fmac_f32_e32 v149, v168, v168
	v_fmac_f32_e32 v174, v176, v176
	v_fmac_f32_e32 v175, v160, v160
	v_fmac_f32_e32 v180, v178, v178
	v_fmac_f32_e32 v169, v170, v170
	v_fmac_f32_e32 v177, v162, v162
	v_fmac_f32_e32 v181, v172, v172
	v_fmac_f32_e32 v182, v164, v164
	v_add_f32_e32 v149, v149, v174
	v_add_f32_e32 v168, v175, v180
	v_add_f32_e32 v169, v169, v177
	v_add_f32_e32 v174, v181, v182
	v_add_f32_e32 v149, v149, v168
	v_add_f32_e32 v168, v169, v174
	v_add_f32_e32 v149, v149, v168
	ds_bpermute_b32 v168, v156, v149
	v_cvt_pk_bf16_f32 v160, v160, v161
	v_cvt_pk_bf16_f32 v161, v178, v179
	global_store_dwordx4 v[166:167], v[158:161], off
	s_waitcnt lgkmcnt(0)
	v_add_f32_e32 v149, v149, v168
	ds_bpermute_b32 v158, v157, v149
	v_cvt_pk_bf16_f32 v160, v170, v171
	v_cvt_pk_bf16_f32 v161, v162, v163
	v_cvt_pk_bf16_f32 v162, v172, v173
	v_cvt_pk_bf16_f32 v163, v164, v165
	global_store_dwordx4 v[166:167], v[160:163], off offset:256
	s_and_saveexec_b64 s[40:41], s[4:5]
	s_load_dwordx16 s[80:95], s[0:1], 0x40
	s_waitcnt lgkmcnt(0)
	s_mov_b64 s[48:49], s[92:93]
	s_mov_b64 s[50:51], s[94:95]
	s_mov_b64 s[46:47], s[90:91]
	s_cbranch_execz .LBB0_802
	v_lshlrev_b64 v[150:151], 6, v[150:151]
	v_lshl_add_u64 v[150:151], s[16:17], 0, v[150:151]
	v_lshl_add_u64 v[150:151], s[38:39], 2, v[150:151]
	s_lshl_b32 s20, s59, 2
	v_lshl_add_u64 v[150:151], v[150:151], 0, s[20:21]
	v_add_f32_e32 v149, v149, v158
	global_store_dword v[150:151], v149, off
.LBB0_802:
	s_or_b64 exec, exec, s[40:41]
	v_or_b32_e32 v150, 48, v148
	v_ashrrev_i32_e32 v151, 31, v150
	v_lshlrev_b64 v[158:159], 11, v[150:151]
	v_lshl_add_u64 v[158:159], s[62:63], 0, v[158:159]
	v_lshl_add_u64 v[166:167], v[146:147], 1, v[158:159]
	s_mov_b64 s[98:99], 0x40000
	v_lshl_add_u64 v[202:203], v[200:201], 0, s[98:99]
	global_load_dwordx4 v[192:195], v[202:203], off
	global_load_dwordx4 v[196:199], v[202:203], off offset:256
	s_waitcnt vmcnt(5)
	v_mov_b32_e32 v158, v184
	v_mov_b32_e32 v159, v185
	v_mov_b32_e32 v160, v186
	v_mov_b32_e32 v161, v187
	v_lshlrev_b32_e32 v168, 16, v158
	v_and_b32_e32 v169, 0xffff0000, v158
	v_lshlrev_b32_e32 v158, 16, v159
	v_and_b32_e32 v159, 0xffff0000, v159
	v_lshlrev_b32_e32 v170, 16, v160
	v_and_b32_e32 v171, 0xffff0000, v160
	v_lshlrev_b32_e32 v160, 16, v161
	v_and_b32_e32 v161, 0xffff0000, v161
	v_mov_b32_e32 v162, v188
	v_mov_b32_e32 v163, v189
	v_mov_b32_e32 v164, v190
	v_mov_b32_e32 v165, v191
	v_lshlrev_b32_e32 v172, 16, v162
	v_and_b32_e32 v173, 0xffff0000, v162
	v_lshlrev_b32_e32 v162, 16, v163
	v_and_b32_e32 v163, 0xffff0000, v163
	v_lshlrev_b32_e32 v174, 16, v164
	v_and_b32_e32 v175, 0xffff0000, v164
	v_lshlrev_b32_e32 v164, 16, v165
	v_and_b32_e32 v165, 0xffff0000, v165
	v_pk_add_f32 v[176:177], v[104:105], v[158:159]
	v_pk_add_f32 v[168:169], v[102:103], v[168:169]
	v_pk_add_f32 v[178:179], v[100:101], v[160:161]
	v_pk_add_f32 v[160:161], v[98:99], v[170:171]
	v_pk_add_f32 v[162:163], v[72:73], v[162:163]
	v_pk_add_f32 v[170:171], v[70:71], v[172:173]
	v_pk_add_f32 v[164:165], v[68:69], v[164:165]
	v_pk_add_f32 v[172:173], v[66:67], v[174:175]
	v_mul_f32_e32 v149, v169, v169
	v_mul_f32_e32 v174, v177, v177
	v_mul_f32_e32 v175, v161, v161
	v_mul_f32_e32 v180, v179, v179
	v_cvt_pk_bf16_f32 v158, v168, v169
	v_cvt_pk_bf16_f32 v159, v176, v177
	v_mul_f32_e32 v169, v171, v171
	v_mul_f32_e32 v177, v163, v163
	v_mul_f32_e32 v181, v173, v173
	v_mul_f32_e32 v182, v165, v165
	v_fmac_f32_e32 v149, v168, v168
	v_fmac_f32_e32 v174, v176, v176
	v_fmac_f32_e32 v175, v160, v160
	v_fmac_f32_e32 v180, v178, v178
	v_fmac_f32_e32 v169, v170, v170
	v_fmac_f32_e32 v177, v162, v162
	v_fmac_f32_e32 v181, v172, v172
	v_fmac_f32_e32 v182, v164, v164
	v_add_f32_e32 v149, v149, v174
	v_add_f32_e32 v168, v175, v180
	v_add_f32_e32 v169, v169, v177
	v_add_f32_e32 v174, v181, v182
	v_add_f32_e32 v149, v149, v168
	v_add_f32_e32 v168, v169, v174
	v_add_f32_e32 v149, v149, v168
	ds_bpermute_b32 v168, v156, v149
	v_cvt_pk_bf16_f32 v160, v160, v161
	v_cvt_pk_bf16_f32 v161, v178, v179
	global_store_dwordx4 v[166:167], v[158:161], off
	s_waitcnt lgkmcnt(0)
	v_add_f32_e32 v149, v149, v168
	ds_bpermute_b32 v158, v157, v149
	v_cvt_pk_bf16_f32 v160, v170, v171
	v_cvt_pk_bf16_f32 v161, v162, v163
	v_cvt_pk_bf16_f32 v162, v172, v173
	v_cvt_pk_bf16_f32 v163, v164, v165
	global_store_dwordx4 v[166:167], v[160:163], off offset:256
	s_and_saveexec_b64 s[40:41], s[4:5]
	s_cbranch_execz .LBB0_804
	v_lshlrev_b64 v[150:151], 6, v[150:151]
	v_lshl_add_u64 v[150:151], s[16:17], 0, v[150:151]
	v_lshl_add_u64 v[150:151], s[38:39], 2, v[150:151]
	s_lshl_b32 s20, s59, 2
	v_lshl_add_u64 v[150:151], v[150:151], 0, s[20:21]
	s_waitcnt lgkmcnt(0)
	v_add_f32_e32 v149, v149, v158
	global_store_dword v[150:151], v149, off
; __device__ __forceinline__ float bflo(unsigned u) { return __uint_as_float(u << 16); }
; __device__ __forceinline__ float bfhi(unsigned u) { return __uint_as_float(u & 0xffff0000u); }
; __device__ __forceinline__ float dot4(f32x4 v) { return (v[0] * v[0] + v[1] * v[1]) + (v[2] * v[2] + v[3] * v[3]); }
; __device__ __forceinline__ u32x2 pack4(f32x4 v) { u32x2 w; w.x = cvt_pk_bf16(v[0], v[1]); w.y = cvt_pk_bf16(v[2], v[3]); return w; }
; __device__ __forceinline__ float quad_sum(float s) { s += __shfl_xor(s, 16); s += __shfl_xor(s, 32); return s; }
; template <int EK>
; __device__ __forceinline__ void epi_tile(const f32x4 (&acc)[2][2][4][2], const Unit& u, int wr, int wc, int fr, int fq, const EpiArgs& E, const LAS float* rt) {
;     ...
;             } else {
;                 float ss = 0.f;
; #pragma unroll
;                 for (int bj = 0; bj < 2; ++bj) { const int col = u.pn * BM + bj * HALF + wc * 32 + fq * 8;
;                     const u32x4 rb = *(const u32x4*)(E.res + (size_t)row * 1024 + col);
;                     const f32x4 x0 = (f32x4){bflo(rb.x), bfhi(rb.x), bflo(rb.y), bfhi(rb.y)} + acc[ai][bj][m][0];
;                     const f32x4 x1 = (f32x4){bflo(rb.z), bfhi(rb.z), bflo(rb.w), bfhi(rb.w)} + acc[ai][bj][m][1]; ss += dot4(x0) + dot4(x1);
;                     const u32x2 lo = pack4(x0), hi = pack4(x1);
;                     *(u32x4*)(E.ob + (size_t)row * 1024 + col) = (u32x4){lo.x, lo.y, hi.x, hi.y}; }
;                 ss = quad_sum(ss); if (fq == 0) E.stOut[(size_t)row * 16 + u.pn * 4 + wc] = ss;
.LBB0_804:
	s_or_b64 exec, exec, s[40:41]
	v_add_u32_e32 v150, 0x80, v148
	v_ashrrev_i32_e32 v151, 31, v150
	s_waitcnt lgkmcnt(0)
	v_lshlrev_b64 v[158:159], 11, v[150:151]
	v_lshl_add_u64 v[158:159], s[62:63], 0, v[158:159]
	v_lshl_add_u64 v[166:167], v[146:147], 1, v[158:159]
	s_mov_b64 s[98:99], 0x48000
	v_lshl_add_u64 v[202:203], v[200:201], 0, s[98:99]
	global_load_dwordx4 v[184:187], v[202:203], off
	global_load_dwordx4 v[188:191], v[202:203], off offset:256
	s_waitcnt vmcnt(5)
	v_mov_b32_e32 v158, v192
	v_mov_b32_e32 v159, v193
	v_mov_b32_e32 v160, v194
	v_mov_b32_e32 v161, v195
	v_lshlrev_b32_e32 v168, 16, v158
	v_and_b32_e32 v169, 0xffff0000, v158
	v_lshlrev_b32_e32 v158, 16, v159
	v_and_b32_e32 v159, 0xffff0000, v159
	v_lshlrev_b32_e32 v170, 16, v160
	v_and_b32_e32 v171, 0xffff0000, v160
	v_lshlrev_b32_e32 v160, 16, v161
	v_and_b32_e32 v161, 0xffff0000, v161
	v_mov_b32_e32 v162, v196
	v_mov_b32_e32 v163, v197
	v_mov_b32_e32 v164, v198
	v_mov_b32_e32 v165, v199
	v_lshlrev_b32_e32 v172, 16, v162
	v_and_b32_e32 v173, 0xffff0000, v162
	v_lshlrev_b32_e32 v162, 16, v163
	v_and_b32_e32 v163, 0xffff0000, v163
	v_lshlrev_b32_e32 v174, 16, v164
	v_and_b32_e32 v175, 0xffff0000, v164
	v_lshlrev_b32_e32 v164, 16, v165
	v_and_b32_e32 v165, 0xffff0000, v165
	v_pk_add_f32 v[176:177], v[64:65], v[158:159]
	v_pk_add_f32 v[168:169], v[62:63], v[168:169]
	v_pk_add_f32 v[178:179], v[60:61], v[160:161]
	v_pk_add_f32 v[160:161], v[58:59], v[170:171]
	v_pk_add_f32 v[162:163], v[32:33], v[162:163]
	v_pk_add_f32 v[170:171], v[30:31], v[172:173]
	v_pk_add_f32 v[164:165], v[28:29], v[164:165]
	v_pk_add_f32 v[172:173], v[26:27], v[174:175]
	v_mul_f32_e32 v149, v169, v169
	v_mul_f32_e32 v174, v177, v177
	v_mul_f32_e32 v175, v161, v161
	v_mul_f32_e32 v180, v179, v179
	v_cvt_pk_bf16_f32 v158, v168, v169
	v_cvt_pk_bf16_f32 v159, v176, v177
	v_mul_f32_e32 v169, v171, v171
	v_mul_f32_e32 v177, v163, v163
	v_mul_f32_e32 v181, v173, v173
	v_mul_f32_e32 v182, v165, v165
	v_fmac_f32_e32 v149, v168, v168
	v_fmac_f32_e32 v174, v176, v176
	v_fmac_f32_e32 v175, v160, v160
	v_fmac_f32_e32 v180, v178, v178
	v_fmac_f32_e32 v169, v170, v170
	v_fmac_f32_e32 v177, v162, v162
	v_fmac_f32_e32 v181, v172, v172
	v_fmac_f32_e32 v182, v164, v164
	v_add_f32_e32 v149, v149, v174
	v_add_f32_e32 v168, v175, v180
	v_add_f32_e32 v169, v169, v177
	v_add_f32_e32 v174, v181, v182
	v_add_f32_e32 v149, v149, v168
	v_add_f32_e32 v168, v169, v174
	v_add_f32_e32 v149, v149, v168
	ds_bpermute_b32 v168, v156, v149
	v_cvt_pk_bf16_f32 v160, v160, v161
	v_cvt_pk_bf16_f32 v161, v178, v179
	global_store_dwordx4 v[166:167], v[158:161], off
	s_waitcnt lgkmcnt(0)
	v_add_f32_e32 v149, v149, v168
	ds_bpermute_b32 v158, v157, v149
	v_cvt_pk_bf16_f32 v160, v170, v171
	v_cvt_pk_bf16_f32 v161, v162, v163
	v_cvt_pk_bf16_f32 v162, v172, v173
	v_cvt_pk_bf16_f32 v163, v164, v165
	global_store_dwordx4 v[166:167], v[160:163], off offset:256
	s_and_saveexec_b64 s[40:41], s[4:5]
	s_cbranch_execz .LBB0_806
	v_lshlrev_b64 v[150:151], 6, v[150:151]
	v_lshl_add_u64 v[150:151], s[16:17], 0, v[150:151]
	v_lshl_add_u64 v[150:151], s[38:39], 2, v[150:151]
	s_lshl_b32 s20, s59, 2
	v_lshl_add_u64 v[150:151], v[150:151], 0, s[20:21]
	s_waitcnt lgkmcnt(0)
	v_add_f32_e32 v149, v149, v158
	global_store_dword v[150:151], v149, off
.LBB0_806:
	s_or_b64 exec, exec, s[40:41]
	v_add_u32_e32 v150, 0x90, v148
	v_ashrrev_i32_e32 v151, 31, v150
	s_waitcnt lgkmcnt(0)
	v_lshlrev_b64 v[158:159], 11, v[150:151]
	v_lshl_add_u64 v[158:159], s[62:63], 0, v[158:159]
	v_lshl_add_u64 v[166:167], v[146:147], 1, v[158:159]
	s_mov_b64 s[98:99], 0x50000
	v_lshl_add_u64 v[202:203], v[200:201], 0, s[98:99]
	global_load_dwordx4 v[192:195], v[202:203], off
	global_load_dwordx4 v[196:199], v[202:203], off offset:256
	s_waitcnt vmcnt(5)
	v_mov_b32_e32 v158, v184
	v_mov_b32_e32 v159, v185
	v_mov_b32_e32 v160, v186
	v_mov_b32_e32 v161, v187
	v_lshlrev_b32_e32 v168, 16, v158
	v_and_b32_e32 v169, 0xffff0000, v158
	v_lshlrev_b32_e32 v158, 16, v159
	v_and_b32_e32 v159, 0xffff0000, v159
	v_lshlrev_b32_e32 v170, 16, v160
	v_and_b32_e32 v171, 0xffff0000, v160
	v_lshlrev_b32_e32 v160, 16, v161
	v_and_b32_e32 v161, 0xffff0000, v161
	v_mov_b32_e32 v162, v188
	v_mov_b32_e32 v163, v189
	v_mov_b32_e32 v164, v190
	v_mov_b32_e32 v165, v191
	v_lshlrev_b32_e32 v172, 16, v162
	v_and_b32_e32 v173, 0xffff0000, v162
	v_lshlrev_b32_e32 v162, 16, v163
	v_and_b32_e32 v163, 0xffff0000, v163
	v_lshlrev_b32_e32 v174, 16, v164
	v_and_b32_e32 v175, 0xffff0000, v164
	v_lshlrev_b32_e32 v164, 16, v165
	v_and_b32_e32 v165, 0xffff0000, v165
	v_pk_add_f32 v[176:177], v[56:57], v[158:159]
	v_pk_add_f32 v[168:169], v[54:55], v[168:169]
	v_pk_add_f32 v[178:179], v[52:53], v[160:161]
	v_pk_add_f32 v[160:161], v[50:51], v[170:171]
	v_pk_add_f32 v[162:163], v[24:25], v[162:163]
	v_pk_add_f32 v[170:171], v[22:23], v[172:173]
	v_pk_add_f32 v[164:165], v[20:21], v[164:165]
	v_pk_add_f32 v[172:173], v[18:19], v[174:175]
	v_mul_f32_e32 v149, v169, v169
	v_mul_f32_e32 v174, v177, v177
	v_mul_f32_e32 v175, v161, v161
	v_mul_f32_e32 v180, v179, v179
	v_cvt_pk_bf16_f32 v158, v168, v169
	v_cvt_pk_bf16_f32 v159, v176, v177
	v_mul_f32_e32 v169, v171, v171
	v_mul_f32_e32 v177, v163, v163
	v_mul_f32_e32 v181, v173, v173
	v_mul_f32_e32 v182, v165, v165
	v_fmac_f32_e32 v149, v168, v168
	v_fmac_f32_e32 v174, v176, v176
	v_fmac_f32_e32 v175, v160, v160
	v_fmac_f32_e32 v180, v178, v178
	v_fmac_f32_e32 v169, v170, v170
	v_fmac_f32_e32 v177, v162, v162
	v_fmac_f32_e32 v181, v172, v172
	v_fmac_f32_e32 v182, v164, v164
	v_add_f32_e32 v149, v149, v174
	v_add_f32_e32 v168, v175, v180
	v_add_f32_e32 v169, v169, v177
	v_add_f32_e32 v174, v181, v182
	v_add_f32_e32 v149, v149, v168
	v_add_f32_e32 v168, v169, v174
	v_add_f32_e32 v149, v149, v168
	ds_bpermute_b32 v168, v156, v149
	v_cvt_pk_bf16_f32 v160, v160, v161
	v_cvt_pk_bf16_f32 v161, v178, v179
	global_store_dwordx4 v[166:167], v[158:161], off
	s_waitcnt lgkmcnt(0)
	v_add_f32_e32 v149, v149, v168
	ds_bpermute_b32 v158, v157, v149
	v_cvt_pk_bf16_f32 v160, v170, v171
	v_cvt_pk_bf16_f32 v161, v162, v163
	v_cvt_pk_bf16_f32 v162, v172, v173
	v_cvt_pk_bf16_f32 v163, v164, v165
	global_store_dwordx4 v[166:167], v[160:163], off offset:256
	s_and_saveexec_b64 s[40:41], s[4:5]
	s_cbranch_execz .LBB0_808
	v_lshlrev_b64 v[150:151], 6, v[150:151]
	v_lshl_add_u64 v[150:151], s[16:17], 0, v[150:151]
	v_lshl_add_u64 v[150:151], s[38:39], 2, v[150:151]
	s_lshl_b32 s20, s59, 2
	v_lshl_add_u64 v[150:151], v[150:151], 0, s[20:21]
	s_waitcnt lgkmcnt(0)
	v_add_f32_e32 v149, v149, v158
	global_store_dword v[150:151], v149, off
; __device__ __forceinline__ float bflo(unsigned u) { return __uint_as_float(u << 16); }
; __device__ __forceinline__ float bfhi(unsigned u) { return __uint_as_float(u & 0xffff0000u); }
; __device__ __forceinline__ float dot4(f32x4 v) { return (v[0] * v[0] + v[1] * v[1]) + (v[2] * v[2] + v[3] * v[3]); }
; __device__ __forceinline__ u32x2 pack4(f32x4 v) { u32x2 w; w.x = cvt_pk_bf16(v[0], v[1]); w.y = cvt_pk_bf16(v[2], v[3]); return w; }
; __device__ __forceinline__ float quad_sum(float s) { s += __shfl_xor(s, 16); s += __shfl_xor(s, 32); return s; }
; template <int EK>
; __device__ __forceinline__ void epi_tile(const f32x4 (&acc)[2][2][4][2], const Unit& u, int wr, int wc, int fr, int fq, const EpiArgs& E, const LAS float* rt) {
;     ...
;             } else {
;                 float ss = 0.f;
; #pragma unroll
;                 for (int bj = 0; bj < 2; ++bj) { const int col = u.pn * BM + bj * HALF + wc * 32 + fq * 8;
;                     const u32x4 rb = *(const u32x4*)(E.res + (size_t)row * 1024 + col);
;                     const f32x4 x0 = (f32x4){bflo(rb.x), bfhi(rb.x), bflo(rb.y), bfhi(rb.y)} + acc[ai][bj][m][0];
;                     const f32x4 x1 = (f32x4){bflo(rb.z), bfhi(rb.z), bflo(rb.w), bfhi(rb.w)} + acc[ai][bj][m][1]; ss += dot4(x0) + dot4(x1);
;                     const u32x2 lo = pack4(x0), hi = pack4(x1);
;                     *(u32x4*)(E.ob + (size_t)row * 1024 + col) = (u32x4){lo.x, lo.y, hi.x, hi.y}; }
;                 ss = quad_sum(ss); if (fq == 0) E.stOut[(size_t)row * 16 + u.pn * 4 + wc] = ss;
.LBB0_808:
	s_or_b64 exec, exec, s[40:41]
	v_add_u32_e32 v150, 0xa0, v148
	v_ashrrev_i32_e32 v151, 31, v150
	s_waitcnt lgkmcnt(0)
	v_lshlrev_b64 v[158:159], 11, v[150:151]
	v_lshl_add_u64 v[158:159], s[62:63], 0, v[158:159]
	v_lshl_add_u64 v[166:167], v[146:147], 1, v[158:159]
	s_mov_b64 s[98:99], 0x58000
	v_lshl_add_u64 v[202:203], v[200:201], 0, s[98:99]
	global_load_dwordx4 v[184:187], v[202:203], off
	global_load_dwordx4 v[188:191], v[202:203], off offset:256
	s_waitcnt vmcnt(5)
	v_mov_b32_e32 v158, v192
	v_mov_b32_e32 v159, v193
	v_mov_b32_e32 v160, v194
	v_mov_b32_e32 v161, v195
	v_lshlrev_b32_e32 v168, 16, v158
	v_and_b32_e32 v169, 0xffff0000, v158
	v_lshlrev_b32_e32 v158, 16, v159
	v_and_b32_e32 v159, 0xffff0000, v159
	v_lshlrev_b32_e32 v170, 16, v160
	v_and_b32_e32 v171, 0xffff0000, v160
	v_lshlrev_b32_e32 v160, 16, v161
	v_and_b32_e32 v161, 0xffff0000, v161
	v_mov_b32_e32 v162, v196
	v_mov_b32_e32 v163, v197
	v_mov_b32_e32 v164, v198
	v_mov_b32_e32 v165, v199
	v_lshlrev_b32_e32 v172, 16, v162
	v_and_b32_e32 v173, 0xffff0000, v162
	v_lshlrev_b32_e32 v162, 16, v163
	v_and_b32_e32 v163, 0xffff0000, v163
	v_lshlrev_b32_e32 v174, 16, v164
	v_and_b32_e32 v175, 0xffff0000, v164
	v_lshlrev_b32_e32 v164, 16, v165
	v_and_b32_e32 v165, 0xffff0000, v165
	v_pk_add_f32 v[176:177], v[48:49], v[158:159]
	v_pk_add_f32 v[168:169], v[46:47], v[168:169]
	v_pk_add_f32 v[178:179], v[44:45], v[160:161]
	v_pk_add_f32 v[160:161], v[42:43], v[170:171]
	v_pk_add_f32 v[162:163], v[16:17], v[162:163]
	v_pk_add_f32 v[170:171], v[14:15], v[172:173]
	v_pk_add_f32 v[164:165], v[12:13], v[164:165]
	v_pk_add_f32 v[172:173], v[10:11], v[174:175]
	v_mul_f32_e32 v149, v169, v169
	v_mul_f32_e32 v174, v177, v177
	v_mul_f32_e32 v175, v161, v161
	v_mul_f32_e32 v180, v179, v179
	v_cvt_pk_bf16_f32 v158, v168, v169
	v_cvt_pk_bf16_f32 v159, v176, v177
	v_mul_f32_e32 v169, v171, v171
	v_mul_f32_e32 v177, v163, v163
	v_mul_f32_e32 v181, v173, v173
	v_mul_f32_e32 v182, v165, v165
	v_fmac_f32_e32 v149, v168, v168
	v_fmac_f32_e32 v174, v176, v176
	v_fmac_f32_e32 v175, v160, v160
	v_fmac_f32_e32 v180, v178, v178
	v_fmac_f32_e32 v169, v170, v170
	v_fmac_f32_e32 v177, v162, v162
	v_fmac_f32_e32 v181, v172, v172
	v_fmac_f32_e32 v182, v164, v164
	v_add_f32_e32 v149, v149, v174
	v_add_f32_e32 v168, v175, v180
	v_add_f32_e32 v169, v169, v177
	v_add_f32_e32 v174, v181, v182
	v_add_f32_e32 v149, v149, v168
	v_add_f32_e32 v168, v169, v174
	v_add_f32_e32 v149, v149, v168
	ds_bpermute_b32 v168, v156, v149
	v_cvt_pk_bf16_f32 v160, v160, v161
	v_cvt_pk_bf16_f32 v161, v178, v179
	global_store_dwordx4 v[166:167], v[158:161], off
	s_waitcnt lgkmcnt(0)
	v_add_f32_e32 v149, v149, v168
	ds_bpermute_b32 v158, v157, v149
	v_cvt_pk_bf16_f32 v160, v170, v171
	v_cvt_pk_bf16_f32 v161, v162, v163
	v_cvt_pk_bf16_f32 v162, v172, v173
	v_cvt_pk_bf16_f32 v163, v164, v165
	global_store_dwordx4 v[166:167], v[160:163], off offset:256
	s_and_saveexec_b64 s[40:41], s[4:5]
	s_cbranch_execz .LBB0_810
	v_lshlrev_b64 v[150:151], 6, v[150:151]
	v_lshl_add_u64 v[150:151], s[16:17], 0, v[150:151]
	v_lshl_add_u64 v[150:151], s[38:39], 2, v[150:151]
	s_lshl_b32 s20, s59, 2
	v_lshl_add_u64 v[150:151], v[150:151], 0, s[20:21]
	s_waitcnt lgkmcnt(0)
	v_add_f32_e32 v149, v149, v158
	global_store_dword v[150:151], v149, off
.LBB0_810:
	s_or_b64 exec, exec, s[40:41]
	v_add_u32_e32 v148, 0xb0, v148
	v_ashrrev_i32_e32 v149, 31, v148
	v_lshlrev_b64 v[150:151], 11, v[148:149]
	v_lshl_add_u64 v[150:151], s[62:63], 0, v[150:151]
	v_lshl_add_u64 v[150:151], v[146:147], 1, v[150:151]
	s_waitcnt lgkmcnt(0)
	s_waitcnt vmcnt(3)
	v_mov_b32_e32 v158, v184
	v_mov_b32_e32 v159, v185
	v_mov_b32_e32 v160, v186
	v_mov_b32_e32 v161, v187
	v_lshlrev_b32_e32 v146, 16, v158
	v_and_b32_e32 v147, 0xffff0000, v158
	v_lshlrev_b32_e32 v158, 16, v159
	v_and_b32_e32 v159, 0xffff0000, v159
	v_lshlrev_b32_e32 v166, 16, v160
	v_and_b32_e32 v167, 0xffff0000, v160
	v_lshlrev_b32_e32 v160, 16, v161
	v_and_b32_e32 v161, 0xffff0000, v161
	v_mov_b32_e32 v162, v188
	v_mov_b32_e32 v163, v189
	v_mov_b32_e32 v164, v190
	v_mov_b32_e32 v165, v191
	v_lshlrev_b32_e32 v168, 16, v162
	v_and_b32_e32 v169, 0xffff0000, v162
	v_lshlrev_b32_e32 v162, 16, v163
	v_and_b32_e32 v163, 0xffff0000, v163
	v_lshlrev_b32_e32 v170, 16, v164
	v_and_b32_e32 v171, 0xffff0000, v164
	v_lshlrev_b32_e32 v164, 16, v165
	v_and_b32_e32 v165, 0xffff0000, v165
	v_pk_add_f32 v[172:173], v[40:41], v[158:159]
	v_pk_add_f32 v[146:147], v[38:39], v[146:147]
	v_pk_add_f32 v[174:175], v[36:37], v[160:161]
	v_pk_add_f32 v[160:161], v[34:35], v[166:167]
	v_pk_add_f32 v[162:163], v[8:9], v[162:163]
	v_pk_add_f32 v[166:167], v[6:7], v[168:169]
	v_pk_add_f32 v[164:165], v[4:5], v[164:165]
	v_pk_add_f32 v[168:169], v[2:3], v[170:171]
	v_mul_f32_e32 v170, v147, v147
	v_mul_f32_e32 v171, v173, v173
	v_mul_f32_e32 v176, v161, v161
	v_mul_f32_e32 v177, v175, v175
	v_cvt_pk_bf16_f32 v158, v146, v147
	v_cvt_pk_bf16_f32 v159, v172, v173
	v_mul_f32_e32 v147, v167, v167
	v_mul_f32_e32 v173, v163, v163
	v_mul_f32_e32 v178, v169, v169
	v_mul_f32_e32 v179, v165, v165
	v_fmac_f32_e32 v170, v146, v146
	v_fmac_f32_e32 v171, v172, v172
	v_fmac_f32_e32 v176, v160, v160
	v_fmac_f32_e32 v177, v174, v174
	v_fmac_f32_e32 v147, v166, v166
	v_fmac_f32_e32 v173, v162, v162
	v_fmac_f32_e32 v178, v168, v168
	v_fmac_f32_e32 v179, v164, v164
	v_add_f32_e32 v146, v170, v171
	v_add_f32_e32 v170, v176, v177
	v_add_f32_e32 v147, v147, v173
	v_add_f32_e32 v171, v178, v179
	v_add_f32_e32 v146, v146, v170
	v_add_f32_e32 v147, v147, v171
	v_add_f32_e32 v146, v146, v147
	ds_bpermute_b32 v147, v156, v146
	v_cvt_pk_bf16_f32 v160, v160, v161
	v_cvt_pk_bf16_f32 v161, v174, v175
	global_store_dwordx4 v[150:151], v[158:161], off
	v_cvt_pk_bf16_f32 v156, v166, v167
	s_waitcnt lgkmcnt(0)
	v_add_f32_e32 v146, v146, v147
	ds_bpermute_b32 v147, v157, v146
	v_cvt_pk_bf16_f32 v157, v162, v163
	v_cvt_pk_bf16_f32 v158, v168, v169
	v_cvt_pk_bf16_f32 v159, v164, v165
	global_store_dwordx4 v[150:151], v[156:159], off offset:256
	s_and_saveexec_b64 s[40:41], s[4:5]
	s_cbranch_execz .LBB0_812
	v_lshlrev_b64 v[148:149], 6, v[148:149]
	v_lshl_add_u64 v[148:149], s[16:17], 0, v[148:149]
	v_lshl_add_u64 v[148:149], s[38:39], 2, v[148:149]
	s_lshl_b32 s20, s59, 2
	v_lshl_add_u64 v[148:149], v[148:149], 0, s[20:21]
	s_waitcnt lgkmcnt(0)
	v_add_f32_e32 v146, v146, v147
	global_store_dword v[148:149], v146, off
